# P0 weight-transpose loop: 16 serialized LDS read+wait+cvt steps batched (8 reads in flight, counted lgkmcnt waits)
# baseline (speedup 1.0000x reference)
.LBB0_15:
	v_ashrrev_i32_e32 v24, 31, v23
	v_add_u32_sdwa v24, v23, v24 dst_sel:DWORD dst_unused:UNUSED_PAD src0_sel:DWORD src1_sel:BYTE_3
	v_ashrrev_i32_e32 v24, 8, v24
	v_mul_i32_i24_e32 v25, 0x100, v24
	v_lshlrev_b32_e32 v40, 6, v24
	v_sub_u32_e32 v24, v23, v25
	v_lshlrev_b32_e32 v25, 5, v25
	v_sub_u32_e32 v43, v7, v25
	v_add_u32_e32 v25, 8, v43
	v_cmp_gt_i32_e32 vcc, s5, v24
	v_or_b32_e32 v26, v40, v1
	v_or_b32_e32 v28, 8, v26
	v_cndmask_b32_e32 v24, v25, v43, vcc
	v_ashrrev_i32_e32 v25, 31, v24
	v_or_b32_e32 v30, 16, v26
	v_or_b32_e32 v31, 24, v26
	v_or_b32_e32 v34, 32, v26
	v_or_b32_e32 v35, 40, v26
	v_or_b32_e32 v38, 48, v26
	v_or_b32_e32 v39, 56, v26
	v_lshl_add_u64 v[24:25], v[24:25], 2, v[4:5]
	v_mad_i64_i32 v[26:27], s[8:9], v26, s6, v[24:25]
	v_mad_i64_i32 v[28:29], s[8:9], v28, s6, v[24:25]
	v_mad_i64_i32 v[32:33], s[8:9], v30, s6, v[24:25]
	v_mad_i64_i32 v[36:37], s[8:9], v31, s6, v[24:25]
	v_mad_i64_i32 v[44:45], s[8:9], v34, s6, v[24:25]
	v_mad_i64_i32 v[48:49], s[8:9], v35, s6, v[24:25]
	v_mad_i64_i32 v[52:53], s[8:9], v38, s6, v[24:25]
	v_mad_i64_i32 v[56:57], s[8:9], v39, s6, v[24:25]
	global_load_dwordx4 v[24:27], v[26:27], off
	s_nop 0
	global_load_dwordx4 v[28:31], v[28:29], off
	s_nop 0
	global_load_dwordx4 v[32:35], v[32:33], off
	s_nop 0
	global_load_dwordx4 v[36:39], v[36:37], off
	s_nop 0
	global_load_dwordx4 v[44:47], v[44:45], off
	s_nop 0
	global_load_dwordx4 v[48:51], v[48:49], off
	s_nop 0
	global_load_dwordx4 v[52:55], v[52:53], off
	s_nop 0
	global_load_dwordx4 v[56:59], v[56:57], off
	v_add_u32_e32 v60, v43, v1
	v_ashrrev_i32_e32 v41, 31, v40
	v_ashrrev_i32_e32 v61, 31, v60
	v_lshl_add_u64 v[40:41], v[40:41], 1, v[2:3]
	v_lshlrev_b64 v[66:67], 11, v[60:61]
	v_add_u32_e32 v62, 8, v60
	v_lshl_add_u64 v[66:67], v[40:41], 0, v[66:67]
	v_ashrrev_i32_e32 v63, 31, v62
	v_lshlrev_b64 v[62:63], 11, v[62:63]
	v_add_u32_e32 v64, 16, v60
	v_lshl_add_u64 v[62:63], v[40:41], 0, v[62:63]
	v_ashrrev_i32_e32 v65, 31, v64
	v_lshlrev_b64 v[64:65], 11, v[64:65]
	v_lshl_add_u64 v[64:65], v[40:41], 0, v[64:65]
	v_add_u32_e32 v23, s33, v23
	v_cmp_lt_i32_e32 vcc, s7, v23
	s_or_b64 s[2:3], vcc, s[2:3]
	v_add_u32_e32 v7, s4, v7
	s_waitcnt vmcnt(7)
	ds_write2_b32 v8, v24, v25 offset1:1
	ds_write2_b32 v8, v26, v27 offset0:2 offset1:3
	s_waitcnt vmcnt(6)
	ds_write2_b32 v9, v28, v29 offset1:1
	ds_write2_b32 v10, v30, v31 offset1:1
	s_waitcnt vmcnt(5)
	ds_write2_b32 v11, v32, v33 offset1:1
	ds_write2_b32 v12, v34, v35 offset1:1
	s_waitcnt vmcnt(4)
	ds_write2_b32 v13, v36, v37 offset1:1
	ds_write2_b32 v14, v38, v39 offset1:1
	s_waitcnt vmcnt(3)
	ds_write2_b32 v15, v44, v45 offset1:1
	ds_write2_b32 v16, v46, v47 offset1:1
	s_waitcnt vmcnt(2)
	ds_write2_b32 v17, v48, v49 offset1:1
	ds_write2_b32 v18, v50, v51 offset1:1
	s_waitcnt vmcnt(1)
	ds_write2_b32 v19, v52, v53 offset1:1
	ds_write2_b32 v20, v54, v55 offset1:1
	s_waitcnt vmcnt(0)
	ds_write2_b32 v21, v56, v57 offset1:1
	ds_write2_b32 v22, v58, v59 offset1:1
	s_waitcnt lgkmcnt(0)
	ds_read2_b32 v[116:117], v6 offset1:33
	ds_read2_b32 v[118:119], v6 offset0:66 offset1:99
	ds_read2_b32 v[120:121], v6 offset0:132 offset1:165
	ds_read2_b32 v[122:123], v6 offset0:198 offset1:231
	ds_read2_b32 v[124:125], v6 offset0:8 offset1:41
	ds_read2_b32 v[126:127], v6 offset0:74 offset1:107
	ds_read2_b32 v[128:129], v6 offset0:140 offset1:173
	ds_read2_b32 v[130:131], v6 offset0:206 offset1:239
	v_add_u32_e32 v30, 24, v60
	v_ashrrev_i32_e32 v31, 31, v30
	v_lshlrev_b64 v[30:31], 11, v[30:31]
	v_lshl_add_u64 v[30:31], v[40:41], 0, v[30:31]
	s_waitcnt lgkmcnt(4)
	v_cvt_pk_bf16_f32 v116, v116, v117
	v_cvt_pk_bf16_f32 v117, v118, v119
	v_cvt_pk_bf16_f32 v118, v120, v121
	v_cvt_pk_bf16_f32 v119, v122, v123
	global_store_dwordx4 v[66:67], v[116:119], off
	ds_read2_b32 v[132:133], v6 offset0:16 offset1:49
	ds_read2_b32 v[134:135], v6 offset0:82 offset1:115
	ds_read2_b32 v[136:137], v6 offset0:148 offset1:181
	ds_read2_b32 v[138:139], v6 offset0:214 offset1:247
	s_waitcnt lgkmcnt(4)
	v_cvt_pk_bf16_f32 v124, v124, v125
	v_cvt_pk_bf16_f32 v125, v126, v127
	v_cvt_pk_bf16_f32 v126, v128, v129
	v_cvt_pk_bf16_f32 v127, v130, v131
	global_store_dwordx4 v[62:63], v[124:127], off
	ds_read2_b32 v[140:141], v6 offset0:24 offset1:57
	ds_read2_b32 v[142:143], v6 offset0:90 offset1:123
	ds_read2_b32 v[144:145], v6 offset0:156 offset1:189
	ds_read2_b32 v[146:147], v6 offset0:222 offset1:255
	s_waitcnt lgkmcnt(4)
	v_cvt_pk_bf16_f32 v132, v132, v133
	v_cvt_pk_bf16_f32 v133, v134, v135
	v_cvt_pk_bf16_f32 v134, v136, v137
	v_cvt_pk_bf16_f32 v135, v138, v139
	global_store_dwordx4 v[64:65], v[132:135], off
	s_waitcnt lgkmcnt(0)
	v_cvt_pk_bf16_f32 v140, v140, v141
	v_cvt_pk_bf16_f32 v141, v142, v143
	v_cvt_pk_bf16_f32 v142, v144, v145
	v_cvt_pk_bf16_f32 v143, v146, v147
	global_store_dwordx4 v[30:31], v[140:143], off
	s_waitcnt lgkmcnt(0)
	s_andn2_b64 exec, exec, s[2:3]
	s_cbranch_execnz .LBB0_15
